# scan fix-up item: the early full waits on the carry loads moved to the first use (loads of the whole chain in flight together)
# speedup vs baseline: 1.0050x; 1.0020x over previous
.LBB0_834:
	s_ashr_i32 s36, s12, 7
	v_mov_b32_e32 v120, 0
	v_mov_b32_e32 v4, v236
	s_bfe_u32 s16, s12, 0x50002
	s_lshl_b32 s13, s36, 13
	s_cmp_lg_u32 s16, 0
	v_or_b32_sdwa v0, v4, s13 dst_sel:DWORD dst_unused:UNUSED_PAD src0_sel:BYTE_0 src1_sel:DWORD
	v_mov_b32_e32 v5, 0
	s_cselect_b64 s[10:11], -1, 0
	s_cmp_eq_u32 s16, 0
	v_ashrrev_i32_e32 v1, 31, v0
	v_mov_b32_e32 v6, 0
	s_cbranch_scc1 .LBB0_836
	v_lshl_add_u64 v[2:3], v[0:1], 2, s[22:23]
	global_load_dword v120, v[2:3], off

.LBB0_840:
	v_mov_b32_e32 v8, 0
	s_andn2_b64 vcc, exec, s[10:11]
	s_cbranch_vccnz .LBB0_842
	v_lshl_add_u64 v[2:3], v[0:1], 2, s[28:29]
	global_load_dword v8, v[2:3], off offset:1024

.LBB0_848:
	v_mov_b32_e32 v12, 0
	s_andn2_b64 vcc, exec, s[10:11]
	s_cbranch_vccnz .LBB0_850
	v_lshl_add_u64 v[2:3], v[0:1], 2, s[28:29]
	global_load_dword v12, v[2:3], off offset:3072

.LBB0_856:
	s_andn2_b64 vcc, exec, s[10:11]
	v_mov_b32_e32 v16, 0
	s_cbranch_vccnz .LBB0_858
	v_lshl_add_u64 v[2:3], v[0:1], 2, s[28:29]
	v_add_co_u32_e32 v2, vcc, 0x1000, v2
	s_nop 1
	v_addc_co_u32_e32 v3, vcc, 0, v3, vcc
	global_load_dword v16, v[2:3], off offset:1024
.LBB0_858:
	s_cmp_gt_u32 s16, 6
	s_cselect_b64 s[10:11], -1, 0
	s_cmp_lt_u32 s16, 7
	v_mov_b32_e32 v17, 1.0
	s_cbranch_scc1 .LBB0_860
	v_lshl_add_u64 v[2:3], v[0:1], 2, s[22:23]
	v_add_co_u32_e32 v2, vcc, 0x1000, v2
	s_nop 1
	v_addc_co_u32_e32 v3, vcc, 0, v3, vcc
	global_load_dword v17, v[2:3], off offset:2048

.LBB0_958:
	s_and_b32 s10, s12, 3
	s_ashr_i32 s37, s36, 31
	v_ashrrev_i32_e32 v25, 8, v4
	s_lshl_b64 s[20:21], s[36:37], 12
	s_lshl_b32 s11, s16, 7
	s_lshl_b32 s16, s10, 5
	v_lshlrev_b32_e32 v0, 4, v25
	s_or_b32 s16, s20, s16
	v_ashrrev_i32_e32 v1, 31, v0
	s_or_b32 s20, s16, s11
	v_lshl_add_u64 v[0:1], s[20:21], 0, v[0:1]
	v_mov_b64_e32 v[2:3], s[26:27]
	v_mad_u64_u32 v[68:69], s[16:17], v0, s18, v[2:3]
	v_mad_i32_i24 v69, v1, s18, v69
	v_lshlrev_b32_sdwa v2, v241, v4 dst_sel:DWORD dst_unused:UNUSED_PAD src0_sel:DWORD src1_sel:BYTE_0
	v_mov_b32_e32 v3, v175
	v_lshl_add_u64 v[68:69], v[68:69], 0, v[2:3]
	s_mov_b32 s11, 0x82b0000
	v_add_co_u32_e32 v70, vcc, s11, v68
	s_mov_b32 s11, 0x82b1000
	s_nop 0
	v_addc_co_u32_e32 v71, vcc, 0, v69, vcc
	global_load_ushort v72, v[70:71], off offset:512 nt
	global_load_ushort v73, v[70:71], off offset:2048 nt
	global_load_ushort v74, v[70:71], off offset:3584 nt
	v_add_co_u32_e32 v70, vcc, s11, v68
	s_waitcnt vmcnt(0)
	v_mul_f32_e32 v6, 0, v120
	v_add_f32_e32 v5, v6, v5
	s_nop 0
	v_addc_co_u32_e32 v71, vcc, 0, v69, vcc
	s_mov_b32 s11, 0x82b2000
	v_fmac_f32_e32 v8, v5, v7
	v_add_co_u32_e32 v6, vcc, s11, v68
	v_fmac_f32_e32 v9, v8, v10
	s_nop 0
	v_addc_co_u32_e32 v7, vcc, 0, v69, vcc
	global_load_ushort v10, v[6:7], off nt
	v_fmac_f32_e32 v12, v9, v11
	global_load_ushort v11, v[6:7], off offset:1536 nt
	s_mov_b32 s11, 0x82b3000
	v_fmac_f32_e32 v14, v12, v13
	global_load_ushort v12, v[6:7], off offset:3072 nt
	v_add_co_u32_e32 v6, vcc, s11, v68
	s_mov_b32 s11, 0x82b4000
	s_nop 0
	v_addc_co_u32_e32 v7, vcc, 0, v69, vcc
	v_fmac_f32_e32 v16, v14, v15
	global_load_ushort v13, v[6:7], off offset:512 nt
	global_load_ushort v14, v[6:7], off offset:2048 nt
	global_load_ushort v15, v[6:7], off offset:3584 nt
	v_add_co_u32_e32 v6, vcc, s11, v68
	s_waitcnt vmcnt(9)
	v_fmac_f32_e32 v18, v16, v17
	v_addc_co_u32_e32 v7, vcc, 0, v69, vcc
	global_load_ushort v17, v[6:7], off offset:1024 nt
	v_fmac_f32_e32 v21, v18, v20
	v_mov_b32_e32 v8, 2
	v_fmac_f32_e32 v23, v21, v22
	v_lshlrev_b32_sdwa v174, v8, v4 dst_sel:DWORD dst_unused:UNUSED_PAD src0_sel:DWORD src1_sel:BYTE_0
	v_fmac_f32_e32 v26, v23, v24
	v_lshl_add_u64 v[20:21], s[30:31], 0, v[174:175]
	v_lshlrev_b64 v[22:23], 10, v[0:1]
	v_fmac_f32_e32 v27, v26, v28
	v_lshl_add_u64 v[8:9], v[20:21], 0, v[22:23]
	global_load_ushort v5, v[70:71], off offset:2560 nt
	v_fmac_f32_e32 v30, v27, v29
	global_load_ushort v18, v[6:7], off offset:2560 nt
	global_load_dword v27, v[8:9], off nt
	s_mov_b32 s11, 0x82b5000
	v_add_co_u32_e32 v6, vcc, s11, v68
	v_fmac_f32_e32 v32, v30, v31
	s_nop 0
	v_addc_co_u32_e32 v7, vcc, 0, v69, vcc
	global_load_ushort v24, v[6:7], off nt
	global_load_ushort v26, v[6:7], off offset:1536 nt
	global_load_ushort v29, v[6:7], off offset:3072 nt
	v_or_b32_e32 v6, 0x400, v22
	v_mov_b32_e32 v7, v23
	v_lshl_add_u64 v[6:7], v[20:21], 0, v[6:7]
	global_load_dword v30, v[6:7], off nt
	v_or_b32_e32 v6, 0x800, v22
	v_mov_b32_e32 v7, v23
	v_lshl_add_u64 v[6:7], v[20:21], 0, v[6:7]
	global_load_ushort v75, v[70:71], off offset:1024 nt
	v_fmac_f32_e32 v34, v32, v33
	global_load_dword v32, v[6:7], off nt
	v_or_b32_e32 v6, 0xc00, v22
	v_mov_b32_e32 v7, v23
	v_lshl_add_u64 v[6:7], v[20:21], 0, v[6:7]
	v_fmac_f32_e32 v36, v34, v35
	global_load_dword v34, v[6:7], off nt
	v_or_b32_e32 v6, 0x1000, v22
	v_mov_b32_e32 v7, v23
	v_lshl_add_u64 v[6:7], v[20:21], 0, v[6:7]
	v_fmac_f32_e32 v38, v36, v37
	global_load_dword v36, v[6:7], off nt
	v_or_b32_e32 v6, 0x1400, v22
	v_mov_b32_e32 v7, v23
	v_lshl_add_u64 v[6:7], v[20:21], 0, v[6:7]
	v_fmac_f32_e32 v40, v38, v39
	global_load_dword v38, v[6:7], off nt
	v_or_b32_e32 v6, 0x1800, v22
	v_mov_b32_e32 v7, v23
	v_lshl_add_u64 v[6:7], v[20:21], 0, v[6:7]
	v_fmac_f32_e32 v42, v40, v41
	global_load_dword v40, v[6:7], off nt
	v_or_b32_e32 v6, 0x1c00, v22
	v_mov_b32_e32 v7, v23
	v_lshl_add_u64 v[6:7], v[20:21], 0, v[6:7]
	v_fmac_f32_e32 v43, v42, v44
	s_waitcnt vmcnt(22)
	v_lshlrev_b32_e32 v28, 16, v72
	global_load_dword v42, v[6:7], off nt
	v_or_b32_e32 v6, 0x2000, v22
	v_mov_b32_e32 v7, v23
	v_lshl_add_u64 v[6:7], v[20:21], 0, v[6:7]
	s_waitcnt vmcnt(19)
	v_lshlrev_b32_e32 v41, 16, v11
	v_mul_f32_e32 v11, 0x3d372713, v28
	global_load_dword v44, v[6:7], off nt
	v_or_b32_e32 v6, 0x2400, v22
	v_mov_b32_e32 v7, v23
	v_mul_f32_e32 v11, v11, v28
	v_fmac_f32_e32 v46, v43, v45
	v_lshl_add_u64 v[6:7], v[20:21], 0, v[6:7]
	v_fma_f32 v11, v11, v28, v28
	v_fmac_f32_e32 v48, v46, v47
	global_load_dword v46, v[6:7], off nt
	v_or_b32_e32 v6, 0x2800, v22
	v_mov_b32_e32 v7, v23
	v_mul_f32_e32 v11, 0x3f4c422a, v11
	v_fmac_f32_e32 v50, v48, v49
	v_lshl_add_u64 v[6:7], v[20:21], 0, v[6:7]
	v_mul_f32_e32 v11, 0xc038aa3b, v11
	v_fmac_f32_e32 v51, v50, v53
	s_waitcnt vmcnt(19)
	v_lshlrev_b32_e32 v45, 16, v13
	global_load_dword v16, v[6:7], off nt
	v_or_b32_e32 v6, 0x2c00, v22
	v_mov_b32_e32 v7, v23
	s_waitcnt vmcnt(17)
	v_lshlrev_b32_e32 v13, 16, v17
	v_exp_f32_e32 v17, v11
	v_fmac_f32_e32 v56, v51, v54
	v_lshl_add_u64 v[6:7], v[20:21], 0, v[6:7]
	v_fmac_f32_e32 v58, v56, v57
	v_lshlrev_b32_e32 v47, 16, v14
	global_load_dword v14, v[6:7], off nt
	v_or_b32_e32 v6, 0x3000, v22
	v_mov_b32_e32 v7, v23
	v_fmac_f32_e32 v60, v58, v59
	v_lshl_add_u64 v[6:7], v[20:21], 0, v[6:7]
	v_fmac_f32_e32 v61, v60, v62
	v_lshlrev_b32_e32 v43, 16, v12
	global_load_dword v12, v[6:7], off nt
	v_or_b32_e32 v6, 0x3400, v22
	v_mov_b32_e32 v7, v23
	v_add_f32_e32 v17, 1.0, v17
	v_fmac_f32_e32 v64, v61, v63
	v_lshl_add_u64 v[6:7], v[20:21], 0, v[6:7]
	v_rcp_f32_e32 v17, v17
	v_fmac_f32_e32 v66, v64, v65
	global_load_dword v9, v[6:7], off nt
	v_or_b32_e32 v6, 0x3800, v22
	v_mov_b32_e32 v7, v23
	v_or_b32_e32 v22, 0x3c00, v22
	v_fmac_f32_e32 v52, v66, v67
	v_lshl_add_u64 v[6:7], v[20:21], 0, v[6:7]
	v_lshl_add_u64 v[20:21], v[20:21], 0, v[22:23]
	s_waitcnt vmcnt(19)
	v_lshlrev_b32_e32 v37, 16, v5
	v_lshlrev_b32_e32 v39, 16, v10
	s_waitcnt vmcnt(18)
	v_lshlrev_b32_e32 v10, 16, v18
	global_load_dword v7, v[6:7], off nt
	v_fmac_f32_e32 v19, v52, v55
	global_load_dword v5, v[20:21], off nt
	s_waitcnt vmcnt(19)
	v_lshlrev_b32_e32 v18, 16, v27
	v_and_b32_e32 v20, 0xffff0000, v27
	v_lshlrev_b32_e32 v31, 16, v73
	v_fmac_f32_e32 v18, v19, v20
	v_mul_f32_e32 v17, v17, v28
	v_mul_f32_e32 v17, v18, v17
	v_mul_f32_e32 v18, 0x3d372713, v31
	v_mul_f32_e32 v18, v18, v31
	v_fma_f32 v18, v18, v31, v31
	v_mul_f32_e32 v18, 0x3f4c422a, v18
	v_mul_f32_e32 v18, 0xc038aa3b, v18
	v_exp_f32_e32 v18, v18
	v_lshl_add_u64 v[2:3], s[34:35], 0, v[2:3]
	v_lshlrev_b64 v[0:1], 11, v[0:1]
	v_cvt_pk_bf16_f32 v17, v17, v175
	v_lshl_add_u64 v[20:21], v[2:3], 0, v[0:1]
	global_store_short v[20:21], v17, off
	v_add_f32_e32 v17, 1.0, v18
	v_rcp_f32_e32 v17, v17
	s_waitcnt vmcnt(16)
	v_lshlrev_b32_e32 v18, 16, v30
	v_and_b32_e32 v20, 0xffff0000, v30
	v_lshlrev_b32_e32 v33, 16, v74
	v_fmac_f32_e32 v18, v19, v20
	v_mul_f32_e32 v17, v17, v31
	v_mul_f32_e32 v17, v18, v17
	v_mul_f32_e32 v18, 0x3d372713, v33
	v_mul_f32_e32 v18, v18, v33
	v_fma_f32 v18, v18, v33, v33
	v_mul_f32_e32 v18, 0x3f4c422a, v18
	v_mul_f32_e32 v18, 0xc038aa3b, v18
	v_exp_f32_e32 v18, v18
	v_or_b32_e32 v20, 0x800, v0
	v_mov_b32_e32 v21, v1
	v_cvt_pk_bf16_f32 v17, v17, v175
	v_lshl_add_u64 v[20:21], v[2:3], 0, v[20:21]
	global_store_short v[20:21], v17, off
	v_add_f32_e32 v17, 1.0, v18
	v_rcp_f32_e32 v17, v17
	s_waitcnt vmcnt(15)
	v_lshlrev_b32_e32 v18, 16, v32
	v_and_b32_e32 v20, 0xffff0000, v32
	v_lshlrev_b32_e32 v35, 16, v75
	v_fmac_f32_e32 v18, v19, v20
	v_mul_f32_e32 v17, v17, v33
	v_mul_f32_e32 v17, v18, v17
	v_mul_f32_e32 v18, 0x3d372713, v35
	v_mul_f32_e32 v18, v18, v35
	v_fma_f32 v18, v18, v35, v35
	v_mul_f32_e32 v18, 0x3f4c422a, v18
	v_mul_f32_e32 v18, 0xc038aa3b, v18
	v_exp_f32_e32 v18, v18
	v_or_b32_e32 v20, 0x1000, v0
	v_mov_b32_e32 v21, v1
	v_cvt_pk_bf16_f32 v17, v17, v175
	v_lshl_add_u64 v[20:21], v[2:3], 0, v[20:21]
	global_store_short v[20:21], v17, off
	v_add_f32_e32 v17, 1.0, v18
	v_rcp_f32_e32 v17, v17
	s_waitcnt vmcnt(15)
	v_lshlrev_b32_e32 v18, 16, v34
	v_and_b32_e32 v20, 0xffff0000, v34
	v_fmac_f32_e32 v18, v19, v20
	v_mul_f32_e32 v17, v17, v35
	v_mul_f32_e32 v17, v18, v17
	v_mul_f32_e32 v18, 0x3d372713, v37
	v_mul_f32_e32 v18, v18, v37
	v_fma_f32 v18, v18, v37, v37
	v_mul_f32_e32 v18, 0x3f4c422a, v18
	v_mul_f32_e32 v18, 0xc038aa3b, v18
	v_exp_f32_e32 v18, v18
	v_or_b32_e32 v20, 0x1800, v0
	v_mov_b32_e32 v21, v1
	v_cvt_pk_bf16_f32 v17, v17, v175
	v_lshl_add_u64 v[20:21], v[2:3], 0, v[20:21]
	global_store_short v[20:21], v17, off
	v_add_f32_e32 v17, 1.0, v18
	v_rcp_f32_e32 v17, v17
	s_waitcnt vmcnt(15)
	v_lshlrev_b32_e32 v18, 16, v36
	v_and_b32_e32 v20, 0xffff0000, v36
	v_fmac_f32_e32 v18, v19, v20
	v_mul_f32_e32 v17, v17, v37
	v_mul_f32_e32 v17, v18, v17
	v_mul_f32_e32 v18, 0x3d372713, v39
	v_mul_f32_e32 v18, v18, v39
	v_fma_f32 v18, v18, v39, v39
	v_mul_f32_e32 v18, 0x3f4c422a, v18
	v_mul_f32_e32 v18, 0xc038aa3b, v18
	v_exp_f32_e32 v18, v18
	v_or_b32_e32 v20, 0x2000, v0
	v_mov_b32_e32 v21, v1
	v_cvt_pk_bf16_f32 v17, v17, v175
	v_lshl_add_u64 v[20:21], v[2:3], 0, v[20:21]
	global_store_short v[20:21], v17, off
	v_add_f32_e32 v17, 1.0, v18
	v_rcp_f32_e32 v17, v17
	s_waitcnt vmcnt(15)
	v_lshlrev_b32_e32 v18, 16, v38
	v_and_b32_e32 v20, 0xffff0000, v38
	v_fmac_f32_e32 v18, v19, v20
	v_mul_f32_e32 v17, v17, v39
	v_mul_f32_e32 v17, v18, v17
	v_mul_f32_e32 v18, 0x3d372713, v41
	v_mul_f32_e32 v18, v18, v41
	v_fma_f32 v18, v18, v41, v41
	v_mul_f32_e32 v18, 0x3f4c422a, v18
	v_mul_f32_e32 v18, 0xc038aa3b, v18
	v_exp_f32_e32 v18, v18
	v_or_b32_e32 v20, 0x2800, v0
	v_mov_b32_e32 v21, v1
	v_cvt_pk_bf16_f32 v17, v17, v175
	v_lshl_add_u64 v[20:21], v[2:3], 0, v[20:21]
	global_store_short v[20:21], v17, off
	v_add_f32_e32 v17, 1.0, v18
	v_rcp_f32_e32 v17, v17
	s_waitcnt vmcnt(15)
	v_lshlrev_b32_e32 v18, 16, v40
	v_and_b32_e32 v20, 0xffff0000, v40
	v_fmac_f32_e32 v18, v19, v20
	v_mul_f32_e32 v17, v17, v41
	v_mul_f32_e32 v17, v18, v17
	v_mul_f32_e32 v18, 0x3d372713, v43
	v_mul_f32_e32 v18, v18, v43
	v_fma_f32 v18, v18, v43, v43
	v_mul_f32_e32 v18, 0x3f4c422a, v18
	v_mul_f32_e32 v18, 0xc038aa3b, v18
	v_exp_f32_e32 v18, v18
	v_or_b32_e32 v20, 0x3000, v0
	v_mov_b32_e32 v21, v1
	v_cvt_pk_bf16_f32 v17, v17, v175
	v_lshl_add_u64 v[20:21], v[2:3], 0, v[20:21]
	global_store_short v[20:21], v17, off
	v_add_f32_e32 v17, 1.0, v18
	v_rcp_f32_e32 v17, v17
	s_waitcnt vmcnt(15)
	v_lshlrev_b32_e32 v18, 16, v42
	v_and_b32_e32 v20, 0xffff0000, v42
	v_fmac_f32_e32 v18, v19, v20
	v_mul_f32_e32 v17, v17, v43
	v_mul_f32_e32 v17, v18, v17
	v_mul_f32_e32 v18, 0x3d372713, v45
	v_mul_f32_e32 v18, v18, v45
	v_fma_f32 v18, v18, v45, v45
	v_mul_f32_e32 v18, 0x3f4c422a, v18
	v_mul_f32_e32 v18, 0xc038aa3b, v18
	v_exp_f32_e32 v18, v18
	v_or_b32_e32 v20, 0x3800, v0
	v_mov_b32_e32 v21, v1
	v_cvt_pk_bf16_f32 v17, v17, v175
	v_lshl_add_u64 v[20:21], v[2:3], 0, v[20:21]
	global_store_short v[20:21], v17, off
	v_add_f32_e32 v17, 1.0, v18
	v_rcp_f32_e32 v17, v17
	s_waitcnt vmcnt(15)
	v_lshlrev_b32_e32 v18, 16, v44
	v_and_b32_e32 v20, 0xffff0000, v44
	v_fmac_f32_e32 v18, v19, v20
	v_mul_f32_e32 v17, v17, v45
	v_mul_f32_e32 v17, v18, v17
	v_mul_f32_e32 v18, 0x3d372713, v47
	v_mul_f32_e32 v18, v18, v47
	v_fma_f32 v18, v18, v47, v47
	v_mul_f32_e32 v18, 0x3f4c422a, v18
	v_mul_f32_e32 v18, 0xc038aa3b, v18
	v_exp_f32_e32 v18, v18
	v_or_b32_e32 v20, 0x4000, v0
	v_mov_b32_e32 v21, v1
	v_cvt_pk_bf16_f32 v17, v17, v175
	v_lshl_add_u64 v[20:21], v[2:3], 0, v[20:21]
	global_store_short v[20:21], v17, off
	v_add_f32_e32 v17, 1.0, v18
	v_rcp_f32_e32 v17, v17
	s_waitcnt vmcnt(15)
	v_lshlrev_b32_e32 v18, 16, v46
	v_and_b32_e32 v20, 0xffff0000, v46
	v_lshlrev_b32_e32 v15, 16, v15
	v_fmac_f32_e32 v18, v19, v20
	v_mul_f32_e32 v17, v17, v47
	v_mul_f32_e32 v17, v18, v17
	v_mul_f32_e32 v18, 0x3d372713, v15
	v_mul_f32_e32 v18, v18, v15
	v_fma_f32 v18, v18, v15, v15
	v_mul_f32_e32 v18, 0x3f4c422a, v18
	v_mul_f32_e32 v18, 0xc038aa3b, v18
	v_exp_f32_e32 v18, v18
	v_or_b32_e32 v20, 0x4800, v0
	v_mov_b32_e32 v21, v1
	v_cvt_pk_bf16_f32 v17, v17, v175
	v_lshl_add_u64 v[20:21], v[2:3], 0, v[20:21]
	global_store_short v[20:21], v17, off
	v_add_f32_e32 v17, 1.0, v18
	v_rcp_f32_e32 v17, v17
	s_waitcnt vmcnt(15)
	v_lshlrev_b32_e32 v18, 16, v16
	v_and_b32_e32 v16, 0xffff0000, v16
	v_fmac_f32_e32 v18, v19, v16
	v_mul_f32_e32 v15, v17, v15
	v_mul_f32_e32 v17, 0x3d372713, v13
	v_mul_f32_e32 v17, v17, v13
	v_fma_f32 v17, v17, v13, v13
	v_mul_f32_e32 v17, 0x3f4c422a, v17
	v_mul_f32_e32 v17, 0xc038aa3b, v17
	v_mul_f32_e32 v15, v18, v15
	v_exp_f32_e32 v18, v17
	v_or_b32_e32 v16, 0x5000, v0
	v_mov_b32_e32 v17, v1
	v_cvt_pk_bf16_f32 v15, v15, v175
	v_lshl_add_u64 v[16:17], v[2:3], 0, v[16:17]
	global_store_short v[16:17], v15, off
	v_add_f32_e32 v15, 1.0, v18
	v_rcp_f32_e32 v15, v15
	s_waitcnt vmcnt(15)
	v_lshlrev_b32_e32 v16, 16, v14
	v_and_b32_e32 v14, 0xffff0000, v14
	v_fmac_f32_e32 v16, v19, v14
	v_mul_f32_e32 v13, v15, v13
	v_mul_f32_e32 v15, 0x3d372713, v10
	v_mul_f32_e32 v15, v15, v10
	v_fma_f32 v15, v15, v10, v10
	v_mul_f32_e32 v15, 0x3f4c422a, v15
	v_mul_f32_e32 v15, 0xc038aa3b, v15
	v_mul_f32_e32 v13, v16, v13
	v_exp_f32_e32 v16, v15
	v_or_b32_e32 v14, 0x5800, v0
	v_mov_b32_e32 v15, v1
	v_cvt_pk_bf16_f32 v13, v13, v175
	v_lshl_add_u64 v[14:15], v[2:3], 0, v[14:15]
	global_store_short v[14:15], v13, off
	v_add_f32_e32 v13, 1.0, v16
	v_rcp_f32_e32 v13, v13
	v_lshlrev_b32_e32 v8, 16, v24
	s_waitcnt vmcnt(15)
	v_lshlrev_b32_e32 v14, 16, v12
	v_and_b32_e32 v12, 0xffff0000, v12
	v_mul_f32_e32 v10, v13, v10
	v_mul_f32_e32 v13, 0x3d372713, v8
	v_mul_f32_e32 v13, v13, v8
	v_fma_f32 v13, v13, v8, v8
	v_mul_f32_e32 v13, 0x3f4c422a, v13
	v_fmac_f32_e32 v14, v19, v12
	v_mul_f32_e32 v13, 0xc038aa3b, v13
	v_mul_f32_e32 v10, v14, v10
	v_exp_f32_e32 v14, v13
	v_or_b32_e32 v12, 0x6000, v0
	v_mov_b32_e32 v13, v1
	v_cvt_pk_bf16_f32 v10, v10, v175
	v_lshl_add_u64 v[12:13], v[2:3], 0, v[12:13]
	v_lshlrev_b32_e32 v6, 16, v26
	global_store_short v[12:13], v10, off
	v_add_f32_e32 v10, 1.0, v14
	s_waitcnt vmcnt(15)
	v_lshlrev_b32_e32 v12, 16, v9
	v_and_b32_e32 v9, 0xffff0000, v9
	v_rcp_f32_e32 v10, v10
	v_fmac_f32_e32 v12, v19, v9
	v_mul_f32_e32 v9, 0x3d372713, v6
	v_mul_f32_e32 v9, v9, v6
	v_fma_f32 v9, v9, v6, v6
	v_mul_f32_e32 v9, 0x3f4c422a, v9
	v_mul_f32_e32 v8, v10, v8
	v_mul_f32_e32 v9, 0xc038aa3b, v9
	v_mul_f32_e32 v8, v12, v8
	v_exp_f32_e32 v12, v9
	v_cvt_pk_bf16_f32 v10, v8, v175
	v_or_b32_e32 v8, 0x6800, v0
	v_mov_b32_e32 v9, v1
	v_lshl_add_u64 v[8:9], v[2:3], 0, v[8:9]
	v_lshlrev_b32_e32 v11, 16, v29
	global_store_short v[8:9], v10, off
	v_add_f32_e32 v8, 1.0, v12
	s_waitcnt vmcnt(15)
	v_lshlrev_b32_e32 v9, 16, v7
	v_and_b32_e32 v7, 0xffff0000, v7
	v_rcp_f32_e32 v8, v8
	v_fmac_f32_e32 v9, v19, v7
	v_mul_f32_e32 v7, 0x3d372713, v11
	v_mul_f32_e32 v7, v7, v11
	v_fma_f32 v7, v7, v11, v11
	v_mul_f32_e32 v7, 0x3f4c422a, v7
	v_mul_f32_e32 v6, v8, v6
	v_mul_f32_e32 v7, 0xc038aa3b, v7
	v_mul_f32_e32 v6, v9, v6
	v_exp_f32_e32 v9, v7
	v_cvt_pk_bf16_f32 v8, v6, v175
	v_or_b32_e32 v6, 0x7000, v0
	v_mov_b32_e32 v7, v1
	v_lshl_add_u64 v[6:7], v[2:3], 0, v[6:7]
	global_store_short v[6:7], v8, off
	v_add_f32_e32 v6, 1.0, v9
	v_rcp_f32_e32 v6, v6
	s_cmp_eq_u32 s10, 3
	s_waitcnt vmcnt(15)
	v_lshlrev_b32_e32 v7, 16, v5
	v_and_b32_e32 v5, 0xffff0000, v5
	s_cselect_b64 s[10:11], -1, 0
	v_cmp_eq_u32_e32 vcc, 1, v25
	v_fmac_f32_e32 v7, v19, v5
	v_mul_f32_e32 v5, v6, v11
	v_or_b32_e32 v0, 0x7800, v0
	s_and_b64 s[10:11], s[10:11], vcc
	v_mul_f32_e32 v5, v7, v5
	v_lshl_add_u64 v[0:1], v[2:3], 0, v[0:1]
	s_and_b64 s[16:17], s[38:39], s[10:11]
	v_cvt_pk_bf16_f32 v5, v5, v175
	global_store_short v[0:1], v5, off
	s_and_saveexec_b64 s[10:11], s[16:17]
	s_cbranch_execz .LBB0_833
	v_or_b32_e32 v0, s13, v4
	v_or_b32_e32 v0, 0x1e00, v0
	v_ashrrev_i32_e32 v1, 31, v0
	v_lshlrev_b64 v[0:1], 2, v[0:1]
	v_lshl_add_u64 v[2:3], s[22:23], 0, v[0:1]
	v_lshl_add_u64 v[0:1], s[28:29], 0, v[0:1]
	global_load_dword v2, v[2:3], off
	s_add_i32 s16, s36, s4
	global_load_dword v3, v[0:1], off
	s_ashr_i32 s17, s16, 31
	s_lshl_b64 s[16:17], s[16:17], 10
	s_add_u32 s16, s24, s16
	s_addc_u32 s17, s25, s17
	v_lshl_add_u64 v[0:1], s[16:17], 0, v[174:175]
	v_add_co_u32_e32 v0, vcc, 0x4180000, v0
	s_waitcnt vmcnt(0)
	v_fmac_f32_e32 v3, v19, v2
	v_addc_co_u32_e32 v1, vcc, 0, v1, vcc
	global_store_dword v[0:1], v3, off
	s_branch .LBB0_833
